# prologue x->bf16 row loop: two rows in flight per wave (next row loads issued before processing the current row)
# speedup vs baseline: 1.0040x; 1.0040x over previous
; __device__ __forceinline__ void phase_prologue(const Params& P, LAS unsigned char* lds, int gw, int ngw, int wid, int lane) {
;     ...
;     for (int row = gw; row < TR; row += ngw) {
;         const float* xr = (row < TP) ? P.in[0] + (size_t)row * DM : P.in[1] + (size_t)(row - TP) * DM;
;         f32x4 v[4]; float s = 0.f;
; #pragma unroll
;         for (int j = 0; j < 4; ++j) { v[j] = __builtin_nontemporal_load((const f32x4*)xr + lane + 64 * j); s += (v[j][0] * v[j][0] + v[j][1] * v[j][1]) + (v[j][2] * v[j][2] + v[j][3] * v[j][3]); }
.LBB0_561:
	s_mov_b32 s36, s10
	s_add_i32 s14, s36, 0xffff8000
	s_lshl_b32 s14, s14, 12
	s_add_u32 s18, s50, s14
	s_addc_u32 s19, s51, 0
	s_cmp_lt_i32 s36, 0x8000
	s_cselect_b32 s18, s12, s18
	s_cselect_b32 s19, s13, s19
	global_load_dwordx4 v[6:9], v4, s[18:19] nt
	global_load_dwordx4 v[10:13], v4, s[18:19] offset:1024 nt
	global_load_dwordx4 v[14:17], v4, s[18:19] offset:2048 nt
	global_load_dwordx4 v[18:21], v4, s[18:19] offset:3072 nt
.Lxb_loop:
	s_add_i32 s36, s10, s20
	s_add_u32 s12, s12, s90
	s_addc_u32 s13, s13, s91
	s_cmp_gt_i32 s36, 0x807f
	s_cselect_b32 s11, 0, 1
	s_cbranch_scc1 .Lxb_w0_a
	s_add_i32 s14, s36, 0xffff8000
	s_lshl_b32 s14, s14, 12
	s_add_u32 s18, s50, s14
	s_addc_u32 s19, s51, 0
	s_cmp_lt_i32 s36, 0x8000
	s_cselect_b32 s18, s12, s18
	s_cselect_b32 s19, s13, s19
	global_load_dwordx4 v[40:43], v4, s[18:19] nt
	global_load_dwordx4 v[44:47], v4, s[18:19] offset:1024 nt
	global_load_dwordx4 v[48:51], v4, s[18:19] offset:2048 nt
	global_load_dwordx4 v[52:55], v4, s[18:19] offset:3072 nt
	s_waitcnt vmcnt(4)
	s_branch .Lxb_p_a

; __device__ __forceinline__ unsigned pk2(float lo, float hi) { const f32x2 v = {lo, hi}; return __builtin_bit_cast(unsigned, __builtin_convertvector(v, hwbf16x2)); }
; __device__ __forceinline__ void phase_prologue(const Params& P, LAS unsigned char* lds, int gw, int ngw, int wid, int lane) {
;     ...
;     for (int row = gw; row < TR; row += ngw) {
;         const float* xr = (row < TP) ? P.in[0] + (size_t)row * DM : P.in[1] + (size_t)(row - TP) * DM;
;         f32x4 v[4]; float s = 0.f;
; #pragma unroll
;         for (int j = 0; j < 4; ++j) { v[j] = __builtin_nontemporal_load((const f32x4*)xr + lane + 64 * j); s += (v[j][0] * v[j][0] + v[j][1] * v[j][1]) + (v[j][2] * v[j][2] + v[j][3] * v[j][3]); }
;         s = wave_sum(s);
; #pragma unroll
;         for (int j = 0; j < 4; ++j) { u32x2 w; w.x = pk2(v[j][0], v[j][1]); w.y = pk2(v[j][2], v[j][3]); ((u32x2*)(Xb + (size_t)row * DM))[lane + 64 * j] = w; }
;         if (lane < 16) ssp[(size_t)row * 16 + lane] = (lane == 0) ? s : 0.f;
.Lxb_p_a:
	s_mov_b32 s16, s10
	s_mov_b32 s17, 0
	s_lshl_b64 s[14:15], s[16:17], 11
	v_lshl_add_u64 v[22:23], v[0:1], 0, s[14:15]
	v_mul_f32_e32 v5, v7, v7
	v_mul_f32_e32 v32, v9, v9
	v_mul_f32_e32 v33, v11, v11
	v_mul_f32_e32 v34, v13, v13
	v_mul_f32_e32 v35, v15, v15
	v_mul_f32_e32 v36, v17, v17
	v_fmac_f32_e32 v5, v6, v6
	v_fmac_f32_e32 v32, v8, v8
	v_fmac_f32_e32 v33, v10, v10
	v_fmac_f32_e32 v34, v12, v12
	v_mul_f32_e32 v37, v19, v19
	v_mul_f32_e32 v38, v21, v21
	v_cvt_pk_bf16_f32 v24, v6, v7
	v_fmac_f32_e32 v35, v14, v14
	v_fmac_f32_e32 v36, v16, v16
	v_add_f32_e32 v5, v5, v32
	v_add_f32_e32 v6, v33, v34
	v_fmac_f32_e32 v37, v18, v18
	v_fmac_f32_e32 v38, v20, v20
	v_add_f32_e32 v7, v35, v36
	v_add_f32_e32 v5, v5, v6
	v_cvt_pk_bf16_f32 v25, v8, v9
	v_add_f32_e32 v8, v37, v38
	v_add_f32_e32 v5, v5, v7
	v_add_f32_e32 v5, v5, v8
	v_cvt_pk_bf16_f32 v30, v18, v19
	v_cvt_pk_bf16_f32 v31, v20, v21
	v_add_f32_dpp v5, v5, v5 quad_perm:[1,0,3,2] row_mask:0xf bank_mask:0xf bound_ctrl:1
	v_cvt_pk_bf16_f32 v26, v10, v11
	v_cvt_pk_bf16_f32 v27, v12, v13
	v_add_f32_dpp v5, v5, v5 quad_perm:[2,3,0,1] row_mask:0xf bank_mask:0xf bound_ctrl:1
	v_cvt_pk_bf16_f32 v28, v14, v15
	v_cvt_pk_bf16_f32 v29, v16, v17
	v_add_f32_dpp v5, v5, v5 row_half_mirror row_mask:0xf bank_mask:0xf bound_ctrl:1
	global_store_dwordx2 v[22:23], v[24:25], off
	global_store_dwordx2 v[22:23], v[26:27], off offset:512
	global_store_dwordx2 v[22:23], v[28:29], off offset:1024
	v_add_f32_dpp v5, v5, v5 row_mirror row_mask:0xf bank_mask:0xf bound_ctrl:1
	global_store_dwordx2 v[22:23], v[30:31], off offset:1536
	v_readlane_b32 s22, v5, 0
	v_readlane_b32 s2, v5, 16
	v_readlane_b32 s23, v5, 32
	v_readlane_b32 s4, v5, 48
	s_and_saveexec_b64 s[18:19], vcc
	s_cbranch_execz .Lxb_ns_a
	v_mov_b32_e32 v6, s2
	v_mov_b32_e32 v7, s4
	v_pk_add_f32 v[6:7], s[22:23], v[6:7]
	s_lshl_b64 s[14:15], s[16:17], 6
	v_add_f32_e32 v5, v6, v7
	v_lshl_add_u64 v[6:7], v[2:3], 0, s[14:15]
	v_cndmask_b32_e64 v5, 0, v5, s[0:1]
	global_store_dword v[6:7], v5, off
.Lxb_ns_a:
	s_or_b64 exec, exec, s[18:19]
	s_cmp_eq_u32 s11, 0
	s_cbranch_scc1 .LBB0_565
	s_mov_b32 s10, s36
	s_add_i32 s36, s10, s20
	s_add_u32 s12, s12, s90
	s_addc_u32 s13, s13, s91
	s_cmp_gt_i32 s36, 0x807f
	s_cselect_b32 s11, 0, 1
	s_cbranch_scc1 .Lxb_w0_b
	s_add_i32 s14, s36, 0xffff8000
	s_lshl_b32 s14, s14, 12
	s_add_u32 s18, s50, s14
	s_addc_u32 s19, s51, 0
	s_cmp_lt_i32 s36, 0x8000
	s_cselect_b32 s18, s12, s18
	s_cselect_b32 s19, s13, s19
	global_load_dwordx4 v[6:9], v4, s[18:19] nt
	global_load_dwordx4 v[10:13], v4, s[18:19] offset:1024 nt
	global_load_dwordx4 v[14:17], v4, s[18:19] offset:2048 nt
	global_load_dwordx4 v[18:21], v4, s[18:19] offset:3072 nt
	s_waitcnt vmcnt(4)
	s_branch .Lxb_p_b

; __device__ __forceinline__ unsigned pk2(float lo, float hi) { const f32x2 v = {lo, hi}; return __builtin_bit_cast(unsigned, __builtin_convertvector(v, hwbf16x2)); }
; __device__ __forceinline__ void phase_prologue(const Params& P, LAS unsigned char* lds, int gw, int ngw, int wid, int lane) {
;     ...
;     for (int row = gw; row < TR; row += ngw) {
;         const float* xr = (row < TP) ? P.in[0] + (size_t)row * DM : P.in[1] + (size_t)(row - TP) * DM;
;         f32x4 v[4]; float s = 0.f;
; #pragma unroll
;         for (int j = 0; j < 4; ++j) { v[j] = __builtin_nontemporal_load((const f32x4*)xr + lane + 64 * j); s += (v[j][0] * v[j][0] + v[j][1] * v[j][1]) + (v[j][2] * v[j][2] + v[j][3] * v[j][3]); }
;         s = wave_sum(s);
; #pragma unroll
;         for (int j = 0; j < 4; ++j) { u32x2 w; w.x = pk2(v[j][0], v[j][1]); w.y = pk2(v[j][2], v[j][3]); ((u32x2*)(Xb + (size_t)row * DM))[lane + 64 * j] = w; }
;         if (lane < 16) ssp[(size_t)row * 16 + lane] = (lane == 0) ? s : 0.f;
.Lxb_p_b:
	s_mov_b32 s16, s10
	s_mov_b32 s17, 0
	s_lshl_b64 s[14:15], s[16:17], 11
	v_lshl_add_u64 v[72:73], v[0:1], 0, s[14:15]
	v_mul_f32_e32 v56, v41, v41
	v_mul_f32_e32 v57, v43, v43
	v_mul_f32_e32 v58, v45, v45
	v_mul_f32_e32 v59, v47, v47
	v_mul_f32_e32 v60, v49, v49
	v_mul_f32_e32 v61, v51, v51
	v_fmac_f32_e32 v56, v40, v40
	v_fmac_f32_e32 v57, v42, v42
	v_fmac_f32_e32 v58, v44, v44
	v_fmac_f32_e32 v59, v46, v46
	v_mul_f32_e32 v62, v53, v53
	v_mul_f32_e32 v63, v55, v55
	v_cvt_pk_bf16_f32 v64, v40, v41
	v_fmac_f32_e32 v60, v48, v48
	v_fmac_f32_e32 v61, v50, v50
	v_add_f32_e32 v56, v56, v57
	v_add_f32_e32 v40, v58, v59
	v_fmac_f32_e32 v62, v52, v52
	v_fmac_f32_e32 v63, v54, v54
	v_add_f32_e32 v41, v60, v61
	v_add_f32_e32 v56, v56, v40
	v_cvt_pk_bf16_f32 v65, v42, v43
	v_add_f32_e32 v42, v62, v63
	v_add_f32_e32 v56, v56, v41
	v_add_f32_e32 v56, v56, v42
	v_cvt_pk_bf16_f32 v70, v52, v53
	v_cvt_pk_bf16_f32 v71, v54, v55
	v_add_f32_dpp v56, v56, v56 quad_perm:[1,0,3,2] row_mask:0xf bank_mask:0xf bound_ctrl:1
	v_cvt_pk_bf16_f32 v66, v44, v45
	v_cvt_pk_bf16_f32 v67, v46, v47
	v_add_f32_dpp v56, v56, v56 quad_perm:[2,3,0,1] row_mask:0xf bank_mask:0xf bound_ctrl:1
	v_cvt_pk_bf16_f32 v68, v48, v49
	v_cvt_pk_bf16_f32 v69, v50, v51
	v_add_f32_dpp v56, v56, v56 row_half_mirror row_mask:0xf bank_mask:0xf bound_ctrl:1
	global_store_dwordx2 v[72:73], v[64:65], off
	global_store_dwordx2 v[72:73], v[66:67], off offset:512
	global_store_dwordx2 v[72:73], v[68:69], off offset:1024
	v_add_f32_dpp v56, v56, v56 row_mirror row_mask:0xf bank_mask:0xf bound_ctrl:1
	global_store_dwordx2 v[72:73], v[70:71], off offset:1536
	v_readlane_b32 s22, v56, 0
	v_readlane_b32 s2, v56, 16
	v_readlane_b32 s23, v56, 32
	v_readlane_b32 s4, v56, 48
	s_and_saveexec_b64 s[18:19], vcc
	s_cbranch_execz .Lxb_ns_b
	v_mov_b32_e32 v40, s2
	v_mov_b32_e32 v41, s4
	v_pk_add_f32 v[40:41], s[22:23], v[40:41]
	s_lshl_b64 s[14:15], s[16:17], 6
	v_add_f32_e32 v56, v40, v41
	v_lshl_add_u64 v[40:41], v[2:3], 0, s[14:15]
	v_cndmask_b32_e64 v56, 0, v56, s[0:1]
	global_store_dword v[40:41], v56, off
.Lxb_ns_b:
	s_or_b64 exec, exec, s[18:19]
	s_cmp_eq_u32 s11, 0
	s_cbranch_scc1 .LBB0_565
	s_mov_b32 s10, s36
	s_branch .Lxb_loop
